# rope-key/V LDS-DMA issue moved from the PV0 head to the end of the QK0 MFMA chain (inside the fragment-read latency window)
# speedup vs baseline: 1.0254x; 1.0032x over previous
; template <int H> __device__ __forceinline__ void qkt_half(f32x16& p, const char* Kn, const char* Kr, const bf16x8* qr, int r32, int hi) {
;   p = f32x16{};
; #pragma unroll
;   for (int d0 = 0; d0 < 8; ++d0) { const int cb = (d0 * 16 + hi * 8) * 2;
;     const bf16x8 f = *reinterpret_cast<const bf16x8*>(Kn + KSWZ(32 * H + r32, cb)); p = __builtin_amdgcn_mfma_f32_32x32x16_bf16(f, qr[d0], p, 0, 0, 0); }
; #pragma unroll
;   for (int d0 = 0; d0 < 4; ++d0) { const int cb = (d0 * 16 + hi * 8) * 2;
;     const bf16x8 f = *reinterpret_cast<const bf16x8*>(Kr + KRSWZ(32 * H + r32, cb)); p = __builtin_amdgcn_mfma_f32_32x32x16_bf16(f, qr[8 + d0], p, 0, 0, 0); }
; }
.LBB0_521:
	ds_read_b128 v[66:69], v187 offset:32768
	ds_read_b128 v[70:73], v188 offset:32768
	ds_read_b128 v[74:77], v189 offset:32768
	ds_read_b128 v[78:81], v190 offset:32768
	v_mfma_f32_32x32x16_bf16 v[82:97], v[250:253], v[252:255], 0
	s_waitcnt lgkmcnt(3)
	v_mfma_f32_32x32x16_bf16 v[82:97], v[66:69], v[98:101], v[82:97]
	ds_read_b128 v[66:69], v191 offset:32768
	s_waitcnt lgkmcnt(3)
	v_mfma_f32_32x32x16_bf16 v[82:97], v[70:73], v[102:105], v[82:97]
	ds_read_b128 v[70:73], v192 offset:32768
	s_waitcnt lgkmcnt(3)
	v_mfma_f32_32x32x16_bf16 v[82:97], v[74:77], v[106:109], v[82:97]
	ds_read_b128 v[74:77], v193 offset:32768
	s_waitcnt lgkmcnt(3)
	v_mfma_f32_32x32x16_bf16 v[82:97], v[78:81], v[110:113], v[82:97]
	ds_read_b128 v[78:81], v194 offset:32768
	s_waitcnt lgkmcnt(3)
	v_mfma_f32_32x32x16_bf16 v[82:97], v[66:69], v[114:117], v[82:97]
	ds_read_b128 v[66:69], v157
	s_waitcnt lgkmcnt(3)
	v_mfma_f32_32x32x16_bf16 v[82:97], v[70:73], v[118:121], v[82:97]
	ds_read_b128 v[70:73], v158
	s_waitcnt lgkmcnt(3)
	v_mfma_f32_32x32x16_bf16 v[82:97], v[74:77], v[122:125], v[82:97]
	ds_read_b128 v[74:77], v159
	s_waitcnt lgkmcnt(3)
	v_mfma_f32_32x32x16_bf16 v[82:97], v[78:81], v[126:129], v[82:97]
	ds_read_b128 v[78:81], v160
	s_waitcnt lgkmcnt(3)
	v_mfma_f32_32x32x16_bf16 v[82:97], v[66:69], v[130:133], v[82:97]
	ds_read_b128 v[66:69], v187 offset:40960
	ds_read_b128 v[168:171], v188 offset:40960
	s_waitcnt lgkmcnt(4)
	v_mfma_f32_32x32x16_bf16 v[82:97], v[70:73], v[134:137], v[82:97]
	ds_read_b128 v[198:201], v189 offset:40960
	ds_read_b128 v[202:205], v190 offset:40960
	s_waitcnt lgkmcnt(5)
	v_mfma_f32_32x32x16_bf16 v[82:97], v[74:77], v[138:141], v[82:97]
	ds_read_b128 v[206:209], v191 offset:40960
	ds_read_b128 v[210:213], v192 offset:40960
	s_waitcnt lgkmcnt(6)
	v_mfma_f32_32x32x16_bf16 v[82:97], v[78:81], v[142:145], v[82:97]
	ds_read_b128 v[214:217], v193 offset:40960
	ds_read_b128 v[218:221], v194 offset:40960
	s_andn2_b64 vcc, exec, s[62:63]
	s_cbranch_vccnz .Ldma_b0_skip
	s_add_i32 m0, s84, 0x12000
	s_nop 0
	global_load_lds_dwordx4 v154, s[20:21]
	s_add_i32 m0, s81, 0x4000
	s_nop 0
	global_load_lds_dwordx4 v155, s[34:35]
	s_add_i32 m0, s81, 0x4400
	s_nop 0
	global_load_lds_dwordx4 v156, s[34:35]
	s_add_u32 s20, s20, 0x2000
	s_addc_u32 s21, s21, 0
	s_add_u32 s34, s34, 0x18000
	s_addc_u32 s35, s35, 0
.Ldma_b0_skip:
	s_nop 3
	s_waitcnt lgkmcnt(2)
	v_mfma_f32_32x32x16_bf16 v[66:81], v[66:69], v[98:101], 0
	ds_read_b128 v[222:225], v157 offset:4096
	ds_read_b128 v[226:229], v158 offset:4096
	ds_read_b128 v[230:233], v159 offset:4096
	ds_read_b128 v[234:237], v160 offset:4096
	v_max_f32_e32 v0, v82, v83
	v_max3_f32 v238, v85, v86, v87
	v_max3_f32 v0, v0, v84, v88
	v_max3_f32 v165, v238, v90, v91
	v_mfma_f32_32x32x16_bf16 v[66:81], v[168:171], v[102:105], v[66:81]
	v_max3_f32 v0, v0, v89, v92
	v_max3_f32 v165, v165, v94, v95
	v_max3_f32 v0, v0, v93, v96
	v_max3_f32 v0, v0, v97, v165
	v_mov_b32_e32 v165, v0
	s_nop 1
	v_permlane32_swap_b32_e32 v0, v165
	v_mfma_f32_32x32x16_bf16 v[66:81], v[198:201], v[106:109], v[66:81]
	v_max_f32_e32 v0, v0, v165
	v_cmp_ge_f32_e32 vcc, s99, v0
	s_cmp_eq_u64 vcc, exec
	s_cbranch_scc0 .Lrare_00
	v_mov_b32_e32 v0, 1.0

; #define VWAIT(N, f) asm volatile("s_waitcnt lgkmcnt(" #N ")" : "+v"(f.l0), "+v"(f.h0), "+v"(f.l1), "+v"(f.h1) :: "memory")
; __device__ __forceinline__ void sm_half(f32x16& p, float& m_reg, float& l_reg, float& alpha, bf16x8& paL, bf16x8& paH) {
;   float a = fmaxf(fmaxf(p[0], p[1]), p[2]), b = fmaxf(fmaxf(p[3], p[4]), p[5]);
;   a = fmaxf(fmaxf(a, p[6]), p[7]); b = fmaxf(fmaxf(b, p[8]), p[9]); a = fmaxf(fmaxf(a, p[10]), p[11]); b = fmaxf(fmaxf(b, p[12]), p[13]); a = fmaxf(fmaxf(a, p[14]), p[15]);
;   float pmax = fmaxf(a, b);
;   { auto rr = __builtin_amdgcn_permlane32_swap(__float_as_uint(pmax), __float_as_uint(pmax), false, false);
;     pmax = fmaxf(__uint_as_float(rr[0]), __uint_as_float(rr[1])); }
;   const bool keep = __all(pmax - m_reg <= THRL);
;   const float mn = keep ? m_reg : fmaxf(m_reg, pmax);
; template <int H> __device__ __forceinline__ void pv_half(f32x16* o, int vb, bf16x8 paL, bf16x8 paH) {
;   VFrag fa = pv_rd<H, 0>(vb), fb = pv_rd<H, 1>(vb);
;   VWAIT(4, fa); pv_mma(o[0], fa, paL, paH);
;   fa = pv_rd<H, 2>(vb);
;   VWAIT(4, fb); pv_mma(o[1], fb, paL, paH);
;   fb = pv_rd<H, 3>(vb);
;   VWAIT(4, fa); pv_mma(o[2], fa, paL, paH);
;   VWAIT(0, fb); pv_mma(o[3], fb, paL, paH);
; }
.LBB0_525:
.LBB0_527:
	ds_read_b64_tr_b16 v[90:91], v175 offset:0
	ds_read_b64_tr_b16 v[92:93], v175 offset:0x800
	ds_read_b64_tr_b16 v[94:95], v175 offset:0x1000
	ds_read_b64_tr_b16 v[96:97], v175 offset:0x1800
	ds_read_b64_tr_b16 v[202:203], v175 offset:0x200
	ds_read_b64_tr_b16 v[204:205], v175 offset:0xa00
	ds_read_b64_tr_b16 v[206:207], v175 offset:0x1200
	ds_read_b64_tr_b16 v[208:209], v175 offset:0x1a00
	s_waitcnt lgkmcnt(4)
	v_mfma_f32_32x32x16_bf16 v[50:65], v[82:85], v[90:93], v[50:65]
	ds_read_b64_tr_b16 v[90:91], v175 offset:0x400
	ds_read_b64_tr_b16 v[92:93], v175 offset:0xc00
	ds_read_b64_tr_b16 v[210:211], v175 offset:0x1400
	ds_read_b64_tr_b16 v[212:213], v175 offset:0x1c00
	s_waitcnt lgkmcnt(4)
	ds_read_b64_tr_b16 v[214:215], v175 offset:0x600
	ds_read_b64_tr_b16 v[216:217], v175 offset:0xe00
	v_mfma_f32_32x32x16_bf16 v[50:65], v[86:89], v[94:97], v[50:65]
	ds_read_b64_tr_b16 v[94:95], v175 offset:0x1600
	ds_read_b64_tr_b16 v[96:97], v175 offset:0x1e00
	s_waitcnt lgkmcnt(4)
	s_waitcnt lgkmcnt(0)
	v_mfma_f32_32x32x16_bf16 v[34:49], v[82:85], v[202:205], v[34:49]
	v_max_f32_e32 v201, v66, v67
	v_max3_f32 v202, v69, v70, v71
	v_max3_f32 v201, v201, v68, v72
	v_max3_f32 v202, v202, v74, v75
	v_max3_f32 v201, v201, v73, v76
	v_max3_f32 v202, v202, v78, v79
	v_max3_f32 v201, v201, v77, v80
	v_max3_f32 v201, v201, v81, v202
	v_mov_b32_e32 v202, v201
	s_nop 1
	v_permlane32_swap_b32_e32 v201, v202
	v_mfma_f32_32x32x16_bf16 v[18:33], v[82:85], v[90:93], v[18:33]
	v_max_f32_e32 v90, v201, v202
	v_cmp_ge_f32_e32 vcc, s99, v90
	s_cmp_eq_u64 vcc, exec
	s_cbranch_scc0 .Lrare_01
	v_mov_b32_e32 v200, 1.0

; template <int H> __device__ __forceinline__ void qkt_half(f32x16& p, const char* Kn, const char* Kr, const bf16x8* qr, int r32, int hi) {
;   p = f32x16{};
; #pragma unroll
;   for (int d0 = 0; d0 < 8; ++d0) { const int cb = (d0 * 16 + hi * 8) * 2;
;     const bf16x8 f = *reinterpret_cast<const bf16x8*>(Kn + KSWZ(32 * H + r32, cb)); p = __builtin_amdgcn_mfma_f32_32x32x16_bf16(f, qr[d0], p, 0, 0, 0); }
; #pragma unroll
;   for (int d0 = 0; d0 < 4; ++d0) { const int cb = (d0 * 16 + hi * 8) * 2;
;     const bf16x8 f = *reinterpret_cast<const bf16x8*>(Kr + KRSWZ(32 * H + r32, cb)); p = __builtin_amdgcn_mfma_f32_32x32x16_bf16(f, qr[8 + d0], p, 0, 0, 0); }
; }
.LBB0_533:
	ds_read_b128 v[66:69], v187 offset:49152
	ds_read_b128 v[70:73], v188 offset:49152
	ds_read_b128 v[74:77], v189 offset:49152
	ds_read_b128 v[78:81], v190 offset:49152
	v_mfma_f32_32x32x16_bf16 v[82:97], v[250:253], v[252:255], 0
	s_waitcnt lgkmcnt(3)
	v_mfma_f32_32x32x16_bf16 v[82:97], v[66:69], v[98:101], v[82:97]
	ds_read_b128 v[66:69], v191 offset:49152
	s_waitcnt lgkmcnt(3)
	v_mfma_f32_32x32x16_bf16 v[82:97], v[70:73], v[102:105], v[82:97]
	ds_read_b128 v[70:73], v192 offset:49152
	s_waitcnt lgkmcnt(3)
	v_mfma_f32_32x32x16_bf16 v[82:97], v[74:77], v[106:109], v[82:97]
	ds_read_b128 v[74:77], v193 offset:49152
	s_waitcnt lgkmcnt(3)
	v_mfma_f32_32x32x16_bf16 v[82:97], v[78:81], v[110:113], v[82:97]
	ds_read_b128 v[78:81], v194 offset:49152
	s_waitcnt lgkmcnt(3)
	v_mfma_f32_32x32x16_bf16 v[82:97], v[66:69], v[114:117], v[82:97]
	ds_read_b128 v[66:69], v157 offset:8192
	s_waitcnt lgkmcnt(3)
	v_mfma_f32_32x32x16_bf16 v[82:97], v[70:73], v[118:121], v[82:97]
	ds_read_b128 v[70:73], v158 offset:8192
	s_waitcnt lgkmcnt(3)
	v_mfma_f32_32x32x16_bf16 v[82:97], v[74:77], v[122:125], v[82:97]
	ds_read_b128 v[74:77], v159 offset:8192
	s_waitcnt lgkmcnt(3)
	v_mfma_f32_32x32x16_bf16 v[82:97], v[78:81], v[126:129], v[82:97]
	ds_read_b128 v[78:81], v160 offset:8192
	s_waitcnt lgkmcnt(3)
	v_mfma_f32_32x32x16_bf16 v[82:97], v[66:69], v[130:133], v[82:97]
	ds_read_b128 v[66:69], v187 offset:57344
	ds_read_b128 v[204:207], v188 offset:57344
	s_waitcnt lgkmcnt(4)
	v_mfma_f32_32x32x16_bf16 v[82:97], v[70:73], v[134:137], v[82:97]
	ds_read_b128 v[208:211], v189 offset:57344
	ds_read_b128 v[212:215], v190 offset:57344
	s_waitcnt lgkmcnt(5)
	v_mfma_f32_32x32x16_bf16 v[82:97], v[74:77], v[138:141], v[82:97]
	ds_read_b128 v[216:219], v191 offset:57344
	ds_read_b128 v[220:223], v192 offset:57344
	s_waitcnt lgkmcnt(6)
	v_mfma_f32_32x32x16_bf16 v[82:97], v[78:81], v[142:145], v[82:97]
	ds_read_b128 v[224:227], v193 offset:57344
	ds_read_b128 v[228:231], v194 offset:57344
	s_andn2_b64 vcc, exec, s[64:65]
	s_cbranch_vccnz .Ldma_b1_skip
	s_mov_b32 m0, s85
	s_nop 0
	global_load_lds_dwordx4 v154, s[20:21]
	s_mov_b32 m0, s81
	s_nop 0
	global_load_lds_dwordx4 v155, s[34:35]
	s_mov_b32 m0, s86
	s_nop 0
	global_load_lds_dwordx4 v156, s[34:35]
	s_add_u32 s20, s20, 0x2000
	s_addc_u32 s21, s21, 0
	s_add_u32 s34, s34, 0x18000
	s_addc_u32 s35, s35, 0
.Ldma_b1_skip:
	s_nop 3
	s_waitcnt lgkmcnt(2)
	v_mfma_f32_32x32x16_bf16 v[66:81], v[66:69], v[98:101], 0
	ds_read_b128 v[232:235], v157 offset:12288
	ds_read_b128 v[236:239], v158 offset:12288
	ds_read_b128 v[240:243], v159 offset:12288
	ds_read_b128 v[244:247], v160 offset:12288
	v_max_f32_e32 v162, v82, v83
	v_max3_f32 v166, v85, v86, v87
	v_max3_f32 v162, v162, v84, v88
	v_max3_f32 v163, v166, v90, v91
	v_mfma_f32_32x32x16_bf16 v[66:81], v[204:207], v[102:105], v[66:81]
	v_max3_f32 v162, v162, v89, v92
	v_max3_f32 v163, v163, v94, v95
	v_max3_f32 v162, v162, v93, v96
	v_max3_f32 v162, v162, v97, v163
	v_mov_b32_e32 v163, v162
	s_nop 1
	v_permlane32_swap_b32_e32 v162, v163
	v_mfma_f32_32x32x16_bf16 v[66:81], v[208:211], v[106:109], v[66:81]
	v_max_f32_e32 v162, v162, v163
	v_cmp_ge_f32_e32 vcc, s99, v162
	s_cmp_eq_u64 vcc, exec
	s_cbranch_scc0 .Lrare_10
	v_mov_b32_e32 v249, 1.0

; #define VWAIT(N, f) asm volatile("s_waitcnt lgkmcnt(" #N ")" : "+v"(f.l0), "+v"(f.h0), "+v"(f.l1), "+v"(f.h1) :: "memory")
; __device__ __forceinline__ void sm_half(f32x16& p, float& m_reg, float& l_reg, float& alpha, bf16x8& paL, bf16x8& paH) {
;   float a = fmaxf(fmaxf(p[0], p[1]), p[2]), b = fmaxf(fmaxf(p[3], p[4]), p[5]);
;   a = fmaxf(fmaxf(a, p[6]), p[7]); b = fmaxf(fmaxf(b, p[8]), p[9]); a = fmaxf(fmaxf(a, p[10]), p[11]); b = fmaxf(fmaxf(b, p[12]), p[13]); a = fmaxf(fmaxf(a, p[14]), p[15]);
;   float pmax = fmaxf(a, b);
;   { auto rr = __builtin_amdgcn_permlane32_swap(__float_as_uint(pmax), __float_as_uint(pmax), false, false);
;     pmax = fmaxf(__uint_as_float(rr[0]), __uint_as_float(rr[1])); }
;   const bool keep = __all(pmax - m_reg <= THRL);
;   const float mn = keep ? m_reg : fmaxf(m_reg, pmax);
; template <int H> __device__ __forceinline__ void pv_half(f32x16* o, int vb, bf16x8 paL, bf16x8 paH) {
;   VFrag fa = pv_rd<H, 0>(vb), fb = pv_rd<H, 1>(vb);
;   VWAIT(4, fa); pv_mma(o[0], fa, paL, paH);
;   fa = pv_rd<H, 2>(vb);
;   VWAIT(4, fb); pv_mma(o[1], fb, paL, paH);
;   fb = pv_rd<H, 3>(vb);
;   VWAIT(4, fa); pv_mma(o[2], fa, paL, paH);
;   VWAIT(0, fb); pv_mma(o[3], fb, paL, paH);
; }
.LBB0_537:
.LBB0_539:
	ds_read_b64_tr_b16 v[94:95], v181 offset:0
	ds_read_b64_tr_b16 v[96:97], v181 offset:0x800
	ds_read_b64_tr_b16 v[164:165], v181 offset:0x1000
	ds_read_b64_tr_b16 v[166:167], v181 offset:0x1800
	ds_read_b64_tr_b16 v[168:169], v181 offset:0x200
	ds_read_b64_tr_b16 v[170:171], v181 offset:0xa00
	ds_read_b64_tr_b16 v[204:205], v181 offset:0x1200
	ds_read_b64_tr_b16 v[206:207], v181 offset:0x1a00
	s_nop 1
	s_waitcnt lgkmcnt(4)
	v_mfma_f32_32x32x16_bf16 v[50:65], v[82:85], v[94:97], v[50:65]
	ds_read_b64_tr_b16 v[94:95], v181 offset:0x400
	ds_read_b64_tr_b16 v[96:97], v181 offset:0xc00
	v_max_f32_e32 v93, v66, v67
	ds_read_b64_tr_b16 v[208:209], v181 offset:0x1400
	v_max3_f32 v163, v69, v70, v71
	v_max3_f32 v93, v93, v68, v72
	ds_read_b64_tr_b16 v[210:211], v181 offset:0x1c00
	v_max3_f32 v163, v163, v74, v75
	v_max3_f32 v93, v93, v73, v76
	s_waitcnt lgkmcnt(4)
	v_max3_f32 v163, v163, v78, v79
	v_max3_f32 v93, v93, v77, v80
	ds_read_b64_tr_b16 v[212:213], v181 offset:0x600
	v_max3_f32 v93, v93, v81, v163
	ds_read_b64_tr_b16 v[214:215], v181 offset:0xe00
	v_mov_b32_e32 v163, v93
	ds_read_b64_tr_b16 v[216:217], v181 offset:0x1600
	s_nop 1
	v_permlane32_swap_b32_e32 v93, v163
	ds_read_b64_tr_b16 v[218:219], v181 offset:0x1e00
	s_waitcnt lgkmcnt(4)
	v_max_f32_e32 v93, v93, v163
	v_mfma_f32_32x32x16_bf16 v[18:33], v[82:85], v[94:97], v[18:33]
	v_cmp_ge_f32_e32 vcc, s99, v93
	s_cmp_eq_u64 vcc, exec
	s_cbranch_scc0 .Lrare_11
	v_mov_b32_e32 v93, 1.0
